# thin_gemm loads remapped so a quarter-wave covers 4 rows x 64B (4x fewer L1 lookups), operands moved to MFMA layout with ds_bpermute; 8 k-steps of loads in flight
# speedup vs baseline: 1.0314x; 1.0084x over previous
.LBB0_687:
	s_waitcnt vmcnt(0)
	v_mov_b32_e32 v0, v177
	v_readlane_b32 s0, v254, 0
	s_cmp_ge_i32 s0, s20
	v_readfirstlane_b32 s2, v0
	s_cbranch_scc1 .LBB0_718
	v_bfe_u32 v38, v0, 2, 4
	v_and_b32_e32 v43, 15, v0
	v_bfe_u32 v140, v0, 4, 2
	v_lshlrev_b32_e32 v43, 4, v43
	v_lshl_or_b32 v43, v140, 2, v43
	s_lshr_b32 s1, s72, 3
	v_and_b32_e32 v1, 63, v0
	s_ashr_i32 s2, s2, 6
	v_or_b32_e32 v2, 0x2000, v38
	v_readlane_b32 s6, v255, 42
	v_lshl_add_u32 v4, v1, 2, 0
	s_mul_i32 s4, s2, s1
	v_lshrrev_b32_e32 v1, 1, v0
	v_mul_u32_u24_e32 v172, s6, v2
	s_lshl_b32 s15, s2, 11
	v_and_b32_e32 v5, 7, v0
	s_mov_b32 s2, 0x3ffffff0
	v_lshl_add_u64 v[2:3], v[172:173], 1, s[64:65]
	v_and_b32_e32 v172, 3, v0
	v_lshlrev_b32_e32 v172, 4, v172
	v_cmp_gt_i32_e64 s[40:41], s97, v0
	v_ashrrev_i32_e32 v39, 3, v0
	v_and_or_b32 v0, v1, s2, v5
	v_lshlrev_b32_e32 v6, 2, v0
	v_or_b32_e32 v7, 0x2000, v5
	v_mov_b64_e32 v[0:1], s[24:25]
	s_movk_i32 s2, 0x1800
	s_ashr_i32 s5, s4, 31
	v_mad_u64_u32 v[0:1], s[26:27], v7, s2, v[0:1]
	s_lshl_b64 s[10:11], s[4:5], 1
	s_mov_b64 s[26:27], 0x1b819800
	v_lshl_add_u64 v[2:3], v[2:3], 0, s[10:11]
	v_lshl_add_u64 v[10:11], v[0:1], 0, s[26:27]
	v_lshlrev_b32_e32 v0, 11, v7
	v_mov_b32_e32 v1, v173
	v_lshl_add_u64 v[8:9], v[2:3], 0, v[172:173]
	v_lshl_add_u64 v[0:1], s[24:25], 0, v[0:1]
	s_mov_b64 s[26:27], 0x19719800
	v_lshlrev_b32_e32 v2, 12, v5
	v_mov_b32_e32 v3, v173
	v_lshl_add_u64 v[12:13], v[0:1], 0, s[26:27]
	s_waitcnt lgkmcnt(0)
	v_lshl_add_u64 v[2:3], s[42:43], 0, v[2:3]
	s_mov_b64 s[26:27], 0x74c4000
	v_lshl_add_u64 v[14:15], v[2:3], 0, s[26:27]
	s_mov_b64 s[26:27], 0x1a799800
	v_lshl_add_u64 v[16:17], v[0:1], 0, s[26:27]
	s_mov_b64 s[26:27], 0x74cc000
	v_mov_b64_e32 v[0:1], s[82:83]
	s_movk_i32 s2, 0x2c00
	v_lshl_add_u64 v[18:19], v[2:3], 0, s[26:27]
	v_mad_u64_u32 v[20:21], s[26:27], v7, s2, v[0:1]
	v_lshlrev_b32_e32 v0, 13, v7
	v_mov_b32_e32 v1, v173
	s_add_u32 s4, s24, 0xd500000
	v_lshl_add_u64 v[0:1], s[24:25], 0, v[0:1]
	s_mov_b64 s[26:27], 0xd700200
	s_addc_u32 s5, s25, 0
	v_lshl_add_u64 v[22:23], v[0:1], 0, s[26:27]
	v_lshlrev_b32_e32 v0, 13, v5
	v_mov_b32_e32 v1, v173
	s_add_u32 s6, s24, 0xd600100
	v_lshl_add_u64 v[24:25], s[8:9], 0, v[0:1]
	v_lshlrev_b32_e32 v0, 8, v7
	s_addc_u32 s7, s25, 0
	v_lshl_add_u64 v[0:1], s[24:25], 0, v[0:1]
	s_mov_b64 s[8:9], 0x13a00200
	s_movk_i32 s2, 0x2600
	v_lshl_add_u64 v[26:27], v[0:1], 0, s[8:9]
	v_mad_u64_u32 v[28:29], s[8:9], v7, s2, v[20:21]
	s_add_u32 s2, s24, s10
	s_addc_u32 s9, s25, s11
	v_readlane_b32 s10, v255, 38
	v_lshlrev_b32_e32 v0, 8, v39
	v_readlane_b32 s11, v255, 39
	s_add_u32 s8, s2, s10
	s_mov_b32 s73, s31
	v_and_b32_e32 v0, 0x300, v0
	s_addc_u32 s9, s9, s11
	v_add3_u32 v40, 0, v6, v0
	v_add3_u32 v41, 0, v0, v6
	v_lshl_add_u64 v[30:31], s[8:9], 0, v[172:173]
	s_lshl_b64 s[26:27], s[72:73], 1
	s_movk_i32 s73, 0x1000
	s_lshl_b32 s2, s0, 4
	s_lshl_b32 s10, s29, 4
	v_add_u32_e32 v42, s15, v4
	s_branch .LBB0_690

.Lthin_chunk:
	s_mov_b32 s9, 0
	s_cmp_ge_u32 s8, 8
	s_cbranch_scc1 .Lthin_L0
	s_sub_u32 s9, 8, s8
	s_lshl_b32 s44, s9, 6
	s_sub_u32 s44, 0, s44
	s_mov_b32 s45, -1
	v_lshl_add_u64 v[32:33], v[32:33], 0, s[44:45]
	v_lshl_add_u64 v[34:35], v[34:35], 0, s[44:45]
	v_lshl_add_u64 v[36:37], v[36:37], 0, s[44:45]
	s_cmp_eq_u32 s9, 1
	s_cbranch_scc1 .Lthin_L1
	s_cmp_eq_u32 s9, 2
	s_cbranch_scc1 .Lthin_L2
	s_cmp_eq_u32 s9, 3
	s_cbranch_scc1 .Lthin_L3
	s_cmp_eq_u32 s9, 4
	s_cbranch_scc1 .Lthin_L4
	s_cmp_eq_u32 s9, 5
	s_cbranch_scc1 .Lthin_L5
	s_cmp_eq_u32 s9, 6
	s_cbranch_scc1 .Lthin_L6
	s_cmp_eq_u32 s9, 7
	s_cbranch_scc1 .Lthin_L7
	s_branch .Lthin_done

.Lthin_L7:
	global_load_dwordx4 v[128:131], v[32:33], off offset:448
	global_load_dwordx4 v[132:135], v[36:37], off offset:448
	global_load_dwordx4 v[136:139], v[34:35], off offset:448
	s_cmp_eq_u32 s9, 1
	s_cbranch_scc1 .Lthin_C1
	s_cmp_eq_u32 s9, 2
	s_cbranch_scc1 .Lthin_C2
	s_cmp_eq_u32 s9, 3
	s_cbranch_scc1 .Lthin_C3
	s_cmp_eq_u32 s9, 4
	s_cbranch_scc1 .Lthin_C4
	s_cmp_eq_u32 s9, 5
	s_cbranch_scc1 .Lthin_C5
	s_cmp_eq_u32 s9, 6
	s_cbranch_scc1 .Lthin_C6
	s_cmp_eq_u32 s9, 7
	s_cbranch_scc1 .Lthin_C7
.Lthin_C0:
	s_waitcnt vmcnt(21)
	ds_bpermute_b32 v44, v43, v44
	ds_bpermute_b32 v45, v43, v45
	ds_bpermute_b32 v46, v43, v46
	ds_bpermute_b32 v47, v43, v47
	ds_bpermute_b32 v48, v43, v48
	ds_bpermute_b32 v49, v43, v49
	ds_bpermute_b32 v50, v43, v50
	ds_bpermute_b32 v51, v43, v51
	ds_bpermute_b32 v52, v43, v52
	ds_bpermute_b32 v53, v43, v53
	ds_bpermute_b32 v54, v43, v54
	ds_bpermute_b32 v55, v43, v55
	s_waitcnt lgkmcnt(4)
	v_mfma_f32_16x16x32_bf16 v[0:3], v[44:47], v[48:51], v[0:3]
	s_waitcnt lgkmcnt(0)
	v_mfma_f32_16x16x32_bf16 v[4:7], v[52:55], v[48:51], v[4:7]
.Lthin_C1:
	s_waitcnt vmcnt(18)
	ds_bpermute_b32 v56, v43, v56
	ds_bpermute_b32 v57, v43, v57
	ds_bpermute_b32 v58, v43, v58
	ds_bpermute_b32 v59, v43, v59
	ds_bpermute_b32 v60, v43, v60
	ds_bpermute_b32 v61, v43, v61
	ds_bpermute_b32 v62, v43, v62
	ds_bpermute_b32 v63, v43, v63
	ds_bpermute_b32 v64, v43, v64
	ds_bpermute_b32 v65, v43, v65
	ds_bpermute_b32 v66, v43, v66
	ds_bpermute_b32 v67, v43, v67
	s_waitcnt lgkmcnt(4)
	v_mfma_f32_16x16x32_bf16 v[0:3], v[56:59], v[60:63], v[0:3]
	s_waitcnt lgkmcnt(0)
	v_mfma_f32_16x16x32_bf16 v[4:7], v[64:67], v[60:63], v[4:7]
.Lthin_C2:
	s_waitcnt vmcnt(15)
	ds_bpermute_b32 v68, v43, v68
	ds_bpermute_b32 v69, v43, v69
	ds_bpermute_b32 v70, v43, v70
	ds_bpermute_b32 v71, v43, v71
	ds_bpermute_b32 v72, v43, v72
	ds_bpermute_b32 v73, v43, v73
	ds_bpermute_b32 v74, v43, v74
	ds_bpermute_b32 v75, v43, v75
	ds_bpermute_b32 v76, v43, v76
	ds_bpermute_b32 v77, v43, v77
	ds_bpermute_b32 v78, v43, v78
	ds_bpermute_b32 v79, v43, v79
	s_waitcnt lgkmcnt(4)
	v_mfma_f32_16x16x32_bf16 v[0:3], v[68:71], v[72:75], v[0:3]
	s_waitcnt lgkmcnt(0)
	v_mfma_f32_16x16x32_bf16 v[4:7], v[76:79], v[72:75], v[4:7]
.Lthin_C3:
	s_waitcnt vmcnt(12)
	ds_bpermute_b32 v80, v43, v80
	ds_bpermute_b32 v81, v43, v81
	ds_bpermute_b32 v82, v43, v82
	ds_bpermute_b32 v83, v43, v83
	ds_bpermute_b32 v84, v43, v84
	ds_bpermute_b32 v85, v43, v85
	ds_bpermute_b32 v86, v43, v86
	ds_bpermute_b32 v87, v43, v87
	ds_bpermute_b32 v88, v43, v88
	ds_bpermute_b32 v89, v43, v89
	ds_bpermute_b32 v90, v43, v90
	ds_bpermute_b32 v91, v43, v91
	s_waitcnt lgkmcnt(4)
	v_mfma_f32_16x16x32_bf16 v[0:3], v[80:83], v[84:87], v[0:3]
	s_waitcnt lgkmcnt(0)
	v_mfma_f32_16x16x32_bf16 v[4:7], v[88:91], v[84:87], v[4:7]
.Lthin_C4:
	s_waitcnt vmcnt(9)
	ds_bpermute_b32 v92, v43, v92
	ds_bpermute_b32 v93, v43, v93
	ds_bpermute_b32 v94, v43, v94
	ds_bpermute_b32 v95, v43, v95
	ds_bpermute_b32 v96, v43, v96
	ds_bpermute_b32 v97, v43, v97
	ds_bpermute_b32 v98, v43, v98
	ds_bpermute_b32 v99, v43, v99
	ds_bpermute_b32 v100, v43, v100
	ds_bpermute_b32 v101, v43, v101
	ds_bpermute_b32 v102, v43, v102
	ds_bpermute_b32 v103, v43, v103
	s_waitcnt lgkmcnt(4)
	v_mfma_f32_16x16x32_bf16 v[0:3], v[92:95], v[96:99], v[0:3]
	s_waitcnt lgkmcnt(0)
	v_mfma_f32_16x16x32_bf16 v[4:7], v[100:103], v[96:99], v[4:7]
.Lthin_C5:
	s_waitcnt vmcnt(6)
	ds_bpermute_b32 v104, v43, v104
	ds_bpermute_b32 v105, v43, v105
	ds_bpermute_b32 v106, v43, v106
	ds_bpermute_b32 v107, v43, v107
	ds_bpermute_b32 v108, v43, v108
	ds_bpermute_b32 v109, v43, v109
	ds_bpermute_b32 v110, v43, v110
	ds_bpermute_b32 v111, v43, v111
	ds_bpermute_b32 v112, v43, v112
	ds_bpermute_b32 v113, v43, v113
	ds_bpermute_b32 v114, v43, v114
	ds_bpermute_b32 v115, v43, v115
	s_waitcnt lgkmcnt(4)
	v_mfma_f32_16x16x32_bf16 v[0:3], v[104:107], v[108:111], v[0:3]
	s_waitcnt lgkmcnt(0)
	v_mfma_f32_16x16x32_bf16 v[4:7], v[112:115], v[108:111], v[4:7]
.Lthin_C6:
	s_waitcnt vmcnt(3)
	ds_bpermute_b32 v116, v43, v116
	ds_bpermute_b32 v117, v43, v117
	ds_bpermute_b32 v118, v43, v118
	ds_bpermute_b32 v119, v43, v119
	ds_bpermute_b32 v120, v43, v120
	ds_bpermute_b32 v121, v43, v121
	ds_bpermute_b32 v122, v43, v122
	ds_bpermute_b32 v123, v43, v123
	ds_bpermute_b32 v124, v43, v124
	ds_bpermute_b32 v125, v43, v125
	ds_bpermute_b32 v126, v43, v126
	ds_bpermute_b32 v127, v43, v127
	s_waitcnt lgkmcnt(4)
	v_mfma_f32_16x16x32_bf16 v[0:3], v[116:119], v[120:123], v[0:3]
	s_waitcnt lgkmcnt(0)
	v_mfma_f32_16x16x32_bf16 v[4:7], v[124:127], v[120:123], v[4:7]
.Lthin_C7:
	s_waitcnt vmcnt(0)
	ds_bpermute_b32 v128, v43, v128
	ds_bpermute_b32 v129, v43, v129
	ds_bpermute_b32 v130, v43, v130
	ds_bpermute_b32 v131, v43, v131
	ds_bpermute_b32 v132, v43, v132
	ds_bpermute_b32 v133, v43, v133
	ds_bpermute_b32 v134, v43, v134
	ds_bpermute_b32 v135, v43, v135
	ds_bpermute_b32 v136, v43, v136
	ds_bpermute_b32 v137, v43, v137
	ds_bpermute_b32 v138, v43, v138
	ds_bpermute_b32 v139, v43, v139
	s_waitcnt lgkmcnt(4)
	v_mfma_f32_16x16x32_bf16 v[0:3], v[128:131], v[132:135], v[0:3]
	s_waitcnt lgkmcnt(0)
	v_mfma_f32_16x16x32_bf16 v[4:7], v[136:139], v[132:135], v[4:7]
	s_cmp_le_u32 s8, 8
	s_cbranch_scc1 .Lthin_done
	s_sub_u32 s8, s8, 8
	s_mov_b64 s[44:45], 0x200
	v_lshl_add_u64 v[32:33], v[32:33], 0, s[44:45]
	v_lshl_add_u64 v[34:35], v[34:35], 0, s[44:45]
	v_lshl_add_u64 v[36:37], v[36:37], 0, s[44:45]
	s_branch .Lthin_chunk
